# line-coalesced residual epilogue at both residual GEMM sites (out-projection and FFN-out)
# speedup vs baseline: 1.0824x; 1.0219x over previous
.LBB0_46:
	v_readlane_b32 s64, v224, 26
	v_readlane_b32 s65, v224, 27
	v_and_b32_e32 v101, 7, v131
	v_bfe_u32 v100, v131, 3, 3
	v_lshrrev_b32_e32 v0, 6, v131
	v_mul_u32_u24_e32 v0, 0x2400, v0
	v_add_u32_e32 v0, 0xa000, v0
	v_and_b32_e32 v98, 31, v131
	v_mul_u32_u24_e32 v98, 0x90, v98
	v_bfe_u32 v99, v131, 5, 1
	v_lshl_add_u32 v98, v99, 4, v98
	v_add_u32_e32 v98, v98, v0
	v_mul_u32_u24_e32 v99, 0x90, v100
	v_lshl_add_u32 v99, v101, 4, v99
	v_add_u32_e32 v99, v99, v0
	s_lshl_b32 s20, s61, 7
	v_and_b32_e32 v0, 64, v114
	v_lshl_add_u32 v101, v101, 2, v0
	v_add_u32_e32 v101, s20, v101
	v_lshlrev_b32_e32 v101, 2, v101
	s_mul_i32 s20, s60, 0xc0
	v_add3_u32 v102, s20, v113, v100
	v_mov_b32_e32 v0, v101
	v_lshl_add_u64 v[116:117], s[14:15], 0, v[0:1]
	s_and_b64 vcc, exec, s[54:55]
	s_cbranch_vccz .Lrt_a_nong
	global_load_dwordx4 v[122:125], v[116:117], off
	global_load_dwordx4 v[126:129], v[116:117], off offset:128

.LBB0_140:
	s_mov_b64 s[74:75], 0x1200
	v_and_b32_e32 v101, 7, v131
	v_bfe_u32 v100, v131, 3, 3
	v_lshrrev_b32_e32 v0, 6, v131
	v_mul_u32_u24_e32 v0, 0x2400, v0
	v_add_u32_e32 v0, 0xa000, v0
	v_and_b32_e32 v98, 31, v131
	v_mul_u32_u24_e32 v98, 0x90, v98
	v_bfe_u32 v99, v131, 5, 1
	v_lshl_add_u32 v98, v99, 4, v98
	v_add_u32_e32 v98, v98, v0
	v_mul_u32_u24_e32 v99, 0x90, v100
	v_lshl_add_u32 v99, v101, 4, v99
	v_add_u32_e32 v99, v99, v0
	s_lshl_b32 s20, s88, 7
	v_and_b32_e32 v0, 64, v114
	v_lshl_add_u32 v101, v101, 2, v0
	v_add_u32_e32 v101, s20, v101
	v_lshlrev_b32_e32 v101, 2, v101
	s_mul_i32 s20, s58, 0xc0
	v_add3_u32 v102, s20, v113, v100
	v_mov_b32_e32 v0, v101
	v_lshl_add_u64 v[116:117], s[14:15], 0, v[0:1]
	s_and_b64 vcc, exec, s[52:53]
	s_cbranch_vccz .Lrt_b_nong
	global_load_dwordx4 v[122:125], v[116:117], off
	global_load_dwordx4 v[126:129], v[116:117], off offset:128
.Lrt_b_nong:
	ds_write_b128 v98, v[82:85] offset:0
	ds_write_b128 v98, v[86:89] offset:32
	ds_write_b128 v98, v[90:93] offset:64
	ds_write_b128 v98, v[94:97] offset:96
	ds_read_b128 v[180:183], v99 offset:0
	ds_read_b128 v[184:187], v99 offset:1152
	ds_read_b128 v[188:191], v99 offset:2304
	ds_read_b128 v[192:195], v99 offset:3456
	v_add_u32_e32 v115, 0, v102
	v_subrev_co_u32_e32 v103, vcc, 0x1000, v115
	v_lshrrev_b32_e32 v103, 11, v103
	v_add_u32_e32 v103, 1, v103
	s_nop 0
	v_cndmask_b32_e64 v103, v103, 0, vcc
	v_add_u32_e32 v0, s46, v103
	v_mul_u32_u24_e32 v0, 0x6000, v0
	v_add_u32_e32 v0, v0, v101
	v_lshl_add_u64 v[116:117], s[48:49], 0, v[0:1]
	global_load_dwordx4 v[212:215], v[116:117], off offset:0
	v_lshlrev_b32_e32 v0, 12, v115
	v_add_u32_e32 v0, v0, v101
	v_lshl_add_u64 v[104:105], s[8:9], 0, v[0:1]
	global_load_dwordx4 v[196:199], v[104:105], off offset:0
	s_and_b64 vcc, exec, s[52:53]
	s_cbranch_vccz .Lrt_b_a_0_0_0
	v_add_u32_e32 v0, s46, v103
	v_mul_u32_u24_e32 v0, 0x6000, v0
	v_add_u32_e32 v0, v0, v101
	v_lshl_add_u64 v[116:117], s[50:51], 0, v[0:1]
	global_load_dwordx4 v[138:141], v[116:117], off offset:0
.Lrt_b_a_0_0_0:
	v_add_u32_e32 v115, 8, v102
	v_subrev_co_u32_e32 v103, vcc, 0x1000, v115
	v_lshrrev_b32_e32 v103, 11, v103
	v_add_u32_e32 v103, 1, v103
	s_nop 0
	v_cndmask_b32_e64 v103, v103, 0, vcc
	v_add_u32_e32 v0, s46, v103
	v_mul_u32_u24_e32 v0, 0x6000, v0
	v_add_u32_e32 v0, v0, v101
	v_lshl_add_u64 v[116:117], s[48:49], 0, v[0:1]
	global_load_dwordx4 v[216:219], v[116:117], off offset:0
	v_lshlrev_b32_e32 v0, 12, v115
	v_add_u32_e32 v0, v0, v101
	v_lshl_add_u64 v[106:107], s[8:9], 0, v[0:1]
	global_load_dwordx4 v[200:203], v[106:107], off offset:0
	s_and_b64 vcc, exec, s[52:53]
	s_cbranch_vccz .Lrt_b_a_0_0_1
	v_add_u32_e32 v0, s46, v103
	v_mul_u32_u24_e32 v0, 0x6000, v0
	v_add_u32_e32 v0, v0, v101
	v_lshl_add_u64 v[116:117], s[50:51], 0, v[0:1]
	global_load_dwordx4 v[142:145], v[116:117], off offset:0
.Lrt_b_a_0_0_1:
	v_add_u32_e32 v115, 16, v102
	v_subrev_co_u32_e32 v103, vcc, 0x1000, v115
	v_lshrrev_b32_e32 v103, 11, v103
	v_add_u32_e32 v103, 1, v103
	s_nop 0
	v_cndmask_b32_e64 v103, v103, 0, vcc
	v_add_u32_e32 v0, s46, v103
	v_mul_u32_u24_e32 v0, 0x6000, v0
	v_add_u32_e32 v0, v0, v101
	v_lshl_add_u64 v[116:117], s[48:49], 0, v[0:1]
	global_load_dwordx4 v[220:223], v[116:117], off offset:0
	v_lshlrev_b32_e32 v0, 12, v115
	v_add_u32_e32 v0, v0, v101
	v_lshl_add_u64 v[108:109], s[8:9], 0, v[0:1]
	global_load_dwordx4 v[204:207], v[108:109], off offset:0
	s_and_b64 vcc, exec, s[52:53]
	s_cbranch_vccz .Lrt_b_a_0_0_2
	v_add_u32_e32 v0, s46, v103
	v_mul_u32_u24_e32 v0, 0x6000, v0
	v_add_u32_e32 v0, v0, v101
	v_lshl_add_u64 v[116:117], s[50:51], 0, v[0:1]
	global_load_dwordx4 v[146:149], v[116:117], off offset:0
.Lrt_b_a_0_0_2:
	v_add_u32_e32 v115, 24, v102
	v_subrev_co_u32_e32 v103, vcc, 0x1000, v115
	v_lshrrev_b32_e32 v103, 11, v103
	v_add_u32_e32 v103, 1, v103
	s_nop 0
	v_cndmask_b32_e64 v103, v103, 0, vcc
	v_add_u32_e32 v0, s46, v103
	v_mul_u32_u24_e32 v0, 0x6000, v0
	v_add_u32_e32 v0, v0, v101
	v_lshl_add_u64 v[116:117], s[48:49], 0, v[0:1]
	global_load_dwordx4 v[134:137], v[116:117], off offset:0
	v_lshlrev_b32_e32 v0, 12, v115
	v_add_u32_e32 v0, v0, v101
	v_lshl_add_u64 v[110:111], s[8:9], 0, v[0:1]
	global_load_dwordx4 v[208:211], v[110:111], off offset:0
	s_and_b64 vcc, exec, s[52:53]
	s_cbranch_vccz .Lrt_b_a_0_0_3
	v_add_u32_e32 v0, s46, v103
	v_mul_u32_u24_e32 v0, 0x6000, v0
	v_add_u32_e32 v0, v0, v101
	v_lshl_add_u64 v[116:117], s[50:51], 0, v[0:1]
	global_load_dwordx4 v[118:121], v[116:117], off offset:0
.Lrt_b_a_0_0_3:
	s_waitcnt vmcnt(0) lgkmcnt(0)
	v_pk_fma_f32 v[196:197], v[180:181], v[212:213], v[196:197]
	v_pk_fma_f32 v[198:199], v[182:183], v[214:215], v[198:199]
	v_pk_fma_f32 v[200:201], v[184:185], v[216:217], v[200:201]
	v_pk_fma_f32 v[202:203], v[186:187], v[218:219], v[202:203]
	v_pk_fma_f32 v[204:205], v[188:189], v[220:221], v[204:205]
	v_pk_fma_f32 v[206:207], v[190:191], v[222:223], v[206:207]
	v_pk_fma_f32 v[208:209], v[192:193], v[134:135], v[208:209]
	v_pk_fma_f32 v[210:211], v[194:195], v[136:137], v[210:211]
	global_store_dwordx4 v[104:105], v[196:199], off offset:0
	global_store_dwordx4 v[106:107], v[200:203], off offset:0
	global_store_dwordx4 v[108:109], v[204:207], off offset:0
	global_store_dwordx4 v[110:111], v[208:211], off offset:0
	s_and_b64 vcc, exec, s[52:53]
	s_cbranch_vccz .Lrt_b_x_0_0
	v_mul_f32_e32 v180, v196, v196
	v_fmac_f32_e32 v180, v197, v197
	v_fmac_f32_e32 v180, v198, v198
	v_fmac_f32_e32 v180, v199, v199
	v_pk_add_f32 v[138:139], v[138:139], 1.0 op_sel_hi:[1,0]
	v_pk_add_f32 v[140:141], v[140:141], 1.0 op_sel_hi:[1,0]
	v_pk_mul_f32 v[196:197], v[196:197], v[122:123]
	v_pk_mul_f32 v[198:199], v[198:199], v[124:125]
	v_pk_mul_f32 v[196:197], v[196:197], v[138:139]
	v_pk_mul_f32 v[198:199], v[198:199], v[140:141]
	v_cvt_pk_f16_f32 v196, v196, v197
	v_cvt_pk_f16_f32 v197, v198, v199
	v_add_u32_e32 v115, 0, v102
	v_lshlrev_b32_e32 v0, 12, v115
	v_add_u32_e32 v0, v0, v101
	v_lshrrev_b32_e32 v0, 1, v0
	v_lshl_add_u64 v[116:117], s[44:45], 0, v[0:1]
	global_store_dwordx2 v[116:117], v[196:197], off offset:0
	v_mul_f32_e32 v184, v200, v200
	v_fmac_f32_e32 v184, v201, v201
	v_fmac_f32_e32 v184, v202, v202
	v_fmac_f32_e32 v184, v203, v203
	v_pk_add_f32 v[142:143], v[142:143], 1.0 op_sel_hi:[1,0]
	v_pk_add_f32 v[144:145], v[144:145], 1.0 op_sel_hi:[1,0]
	v_pk_mul_f32 v[200:201], v[200:201], v[122:123]
	v_pk_mul_f32 v[202:203], v[202:203], v[124:125]
	v_pk_mul_f32 v[200:201], v[200:201], v[142:143]
	v_pk_mul_f32 v[202:203], v[202:203], v[144:145]
	v_cvt_pk_f16_f32 v200, v200, v201
	v_cvt_pk_f16_f32 v201, v202, v203
	v_add_u32_e32 v115, 8, v102
	v_lshlrev_b32_e32 v0, 12, v115
	v_add_u32_e32 v0, v0, v101
	v_lshrrev_b32_e32 v0, 1, v0
	v_lshl_add_u64 v[116:117], s[44:45], 0, v[0:1]
	global_store_dwordx2 v[116:117], v[200:201], off offset:0
	v_mul_f32_e32 v188, v204, v204
	v_fmac_f32_e32 v188, v205, v205
	v_fmac_f32_e32 v188, v206, v206
	v_fmac_f32_e32 v188, v207, v207
	v_pk_add_f32 v[146:147], v[146:147], 1.0 op_sel_hi:[1,0]
	v_pk_add_f32 v[148:149], v[148:149], 1.0 op_sel_hi:[1,0]
	v_pk_mul_f32 v[204:205], v[204:205], v[122:123]
	v_pk_mul_f32 v[206:207], v[206:207], v[124:125]
	v_pk_mul_f32 v[204:205], v[204:205], v[146:147]
	v_pk_mul_f32 v[206:207], v[206:207], v[148:149]
	v_cvt_pk_f16_f32 v204, v204, v205
	v_cvt_pk_f16_f32 v205, v206, v207
	v_add_u32_e32 v115, 16, v102
	v_lshlrev_b32_e32 v0, 12, v115
	v_add_u32_e32 v0, v0, v101
	v_lshrrev_b32_e32 v0, 1, v0
	v_lshl_add_u64 v[116:117], s[44:45], 0, v[0:1]
	global_store_dwordx2 v[116:117], v[204:205], off offset:0
	v_mul_f32_e32 v192, v208, v208
	v_fmac_f32_e32 v192, v209, v209
	v_fmac_f32_e32 v192, v210, v210
	v_fmac_f32_e32 v192, v211, v211
	v_pk_add_f32 v[118:119], v[118:119], 1.0 op_sel_hi:[1,0]
	v_pk_add_f32 v[120:121], v[120:121], 1.0 op_sel_hi:[1,0]
	v_pk_mul_f32 v[208:209], v[208:209], v[122:123]
	v_pk_mul_f32 v[210:211], v[210:211], v[124:125]
	v_pk_mul_f32 v[208:209], v[208:209], v[118:119]
	v_pk_mul_f32 v[210:211], v[210:211], v[120:121]
	v_cvt_pk_f16_f32 v208, v208, v209
	v_cvt_pk_f16_f32 v209, v210, v211
	v_add_u32_e32 v115, 24, v102
	v_lshlrev_b32_e32 v0, 12, v115
	v_add_u32_e32 v0, v0, v101
	v_lshrrev_b32_e32 v0, 1, v0
	v_lshl_add_u64 v[116:117], s[44:45], 0, v[0:1]
	global_store_dwordx2 v[116:117], v[208:209], off offset:0
	s_nop 1
	v_add_f32_dpp v180, v180, v180 quad_perm:[1,0,3,2] row_mask:0xf bank_mask:0xf bound_ctrl:1
	v_add_f32_dpp v184, v184, v184 quad_perm:[1,0,3,2] row_mask:0xf bank_mask:0xf bound_ctrl:1
	v_add_f32_dpp v188, v188, v188 quad_perm:[1,0,3,2] row_mask:0xf bank_mask:0xf bound_ctrl:1
	v_add_f32_dpp v192, v192, v192 quad_perm:[1,0,3,2] row_mask:0xf bank_mask:0xf bound_ctrl:1
	s_nop 1
	v_add_f32_dpp v180, v180, v180 quad_perm:[2,3,0,1] row_mask:0xf bank_mask:0xf bound_ctrl:1
	v_add_f32_dpp v184, v184, v184 quad_perm:[2,3,0,1] row_mask:0xf bank_mask:0xf bound_ctrl:1
	v_add_f32_dpp v188, v188, v188 quad_perm:[2,3,0,1] row_mask:0xf bank_mask:0xf bound_ctrl:1
	v_add_f32_dpp v192, v192, v192 quad_perm:[2,3,0,1] row_mask:0xf bank_mask:0xf bound_ctrl:1
	s_nop 1
	v_add_f32_dpp v180, v180, v180 row_half_mirror row_mask:0xf bank_mask:0xf bound_ctrl:1
	v_add_f32_dpp v184, v184, v184 row_half_mirror row_mask:0xf bank_mask:0xf bound_ctrl:1
	v_add_f32_dpp v188, v188, v188 row_half_mirror row_mask:0xf bank_mask:0xf bound_ctrl:1
	v_add_f32_dpp v192, v192, v192 row_half_mirror row_mask:0xf bank_mask:0xf bound_ctrl:1
	s_mov_b64 s[42:43], exec
	s_mov_b32 s20, 0x01010101
	s_mov_b32 exec_lo, s20
	s_mov_b32 exec_hi, s20
	v_add_u32_e32 v0, 0, v102
	v_lshlrev_b32_e32 v0, 2, v0
	v_lshl_add_u64 v[116:117], s[12:13], 0, v[0:1]
	global_atomic_add_f32 v[116:117], v180, off
	v_add_u32_e32 v0, 8, v102
	v_lshlrev_b32_e32 v0, 2, v0
	v_lshl_add_u64 v[116:117], s[12:13], 0, v[0:1]
	global_atomic_add_f32 v[116:117], v184, off
	v_add_u32_e32 v0, 16, v102
	v_lshlrev_b32_e32 v0, 2, v0
	v_lshl_add_u64 v[116:117], s[12:13], 0, v[0:1]
	global_atomic_add_f32 v[116:117], v188, off
	v_add_u32_e32 v0, 24, v102
	v_lshlrev_b32_e32 v0, 2, v0
	v_lshl_add_u64 v[116:117], s[12:13], 0, v[0:1]
	global_atomic_add_f32 v[116:117], v192, off
	s_mov_b64 exec, s[42:43]
.Lrt_b_x_0_0:
	ds_write_b128 v98, v[66:69] offset:4608
	ds_write_b128 v98, v[70:73] offset:4640
	ds_write_b128 v98, v[74:77] offset:4672
	ds_write_b128 v98, v[78:81] offset:4704
	ds_read_b128 v[180:183], v99 offset:4608
	ds_read_b128 v[184:187], v99 offset:5760
	ds_read_b128 v[188:191], v99 offset:6912
	ds_read_b128 v[192:195], v99 offset:8064
	v_add_u32_e32 v115, 0, v102
	v_subrev_co_u32_e32 v103, vcc, 0x1000, v115
	v_lshrrev_b32_e32 v103, 11, v103
	v_add_u32_e32 v103, 1, v103
	s_nop 0
	v_cndmask_b32_e64 v103, v103, 0, vcc
	v_add_u32_e32 v0, s46, v103
	v_mul_u32_u24_e32 v0, 0x6000, v0
	v_add_u32_e32 v0, v0, v101
	v_lshl_add_u64 v[116:117], s[48:49], 0, v[0:1]
	global_load_dwordx4 v[212:215], v[116:117], off offset:128
	v_lshlrev_b32_e32 v0, 12, v115
	v_add_u32_e32 v0, v0, v101
	v_lshl_add_u64 v[104:105], s[8:9], 0, v[0:1]
	global_load_dwordx4 v[196:199], v[104:105], off offset:128
	s_and_b64 vcc, exec, s[52:53]
	s_cbranch_vccz .Lrt_b_a_0_1_0
	v_add_u32_e32 v0, s46, v103
	v_mul_u32_u24_e32 v0, 0x6000, v0
	v_add_u32_e32 v0, v0, v101
	v_lshl_add_u64 v[116:117], s[50:51], 0, v[0:1]
	global_load_dwordx4 v[138:141], v[116:117], off offset:128
.Lrt_b_a_0_1_0:
	v_add_u32_e32 v115, 8, v102
	v_subrev_co_u32_e32 v103, vcc, 0x1000, v115
	v_lshrrev_b32_e32 v103, 11, v103
	v_add_u32_e32 v103, 1, v103
	s_nop 0
	v_cndmask_b32_e64 v103, v103, 0, vcc
	v_add_u32_e32 v0, s46, v103
	v_mul_u32_u24_e32 v0, 0x6000, v0
	v_add_u32_e32 v0, v0, v101
	v_lshl_add_u64 v[116:117], s[48:49], 0, v[0:1]
	global_load_dwordx4 v[216:219], v[116:117], off offset:128
	v_lshlrev_b32_e32 v0, 12, v115
	v_add_u32_e32 v0, v0, v101
	v_lshl_add_u64 v[106:107], s[8:9], 0, v[0:1]
	global_load_dwordx4 v[200:203], v[106:107], off offset:128
	s_and_b64 vcc, exec, s[52:53]
	s_cbranch_vccz .Lrt_b_a_0_1_1
	v_add_u32_e32 v0, s46, v103
	v_mul_u32_u24_e32 v0, 0x6000, v0
	v_add_u32_e32 v0, v0, v101
	v_lshl_add_u64 v[116:117], s[50:51], 0, v[0:1]
	global_load_dwordx4 v[142:145], v[116:117], off offset:128
.Lrt_b_a_0_1_1:
	v_add_u32_e32 v115, 16, v102
	v_subrev_co_u32_e32 v103, vcc, 0x1000, v115
	v_lshrrev_b32_e32 v103, 11, v103
	v_add_u32_e32 v103, 1, v103
	s_nop 0
	v_cndmask_b32_e64 v103, v103, 0, vcc
	v_add_u32_e32 v0, s46, v103
	v_mul_u32_u24_e32 v0, 0x6000, v0
	v_add_u32_e32 v0, v0, v101
	v_lshl_add_u64 v[116:117], s[48:49], 0, v[0:1]
	global_load_dwordx4 v[220:223], v[116:117], off offset:128
	v_lshlrev_b32_e32 v0, 12, v115
	v_add_u32_e32 v0, v0, v101
	v_lshl_add_u64 v[108:109], s[8:9], 0, v[0:1]
	global_load_dwordx4 v[204:207], v[108:109], off offset:128
	s_and_b64 vcc, exec, s[52:53]
	s_cbranch_vccz .Lrt_b_a_0_1_2
	v_add_u32_e32 v0, s46, v103
	v_mul_u32_u24_e32 v0, 0x6000, v0
	v_add_u32_e32 v0, v0, v101
	v_lshl_add_u64 v[116:117], s[50:51], 0, v[0:1]
	global_load_dwordx4 v[146:149], v[116:117], off offset:128
.Lrt_b_a_0_1_2:
	v_add_u32_e32 v115, 24, v102
	v_subrev_co_u32_e32 v103, vcc, 0x1000, v115
	v_lshrrev_b32_e32 v103, 11, v103
	v_add_u32_e32 v103, 1, v103
	s_nop 0
	v_cndmask_b32_e64 v103, v103, 0, vcc
	v_add_u32_e32 v0, s46, v103
	v_mul_u32_u24_e32 v0, 0x6000, v0
	v_add_u32_e32 v0, v0, v101
	v_lshl_add_u64 v[116:117], s[48:49], 0, v[0:1]
	global_load_dwordx4 v[134:137], v[116:117], off offset:128
	v_lshlrev_b32_e32 v0, 12, v115
	v_add_u32_e32 v0, v0, v101
	v_lshl_add_u64 v[110:111], s[8:9], 0, v[0:1]
	global_load_dwordx4 v[208:211], v[110:111], off offset:128
	s_and_b64 vcc, exec, s[52:53]
	s_cbranch_vccz .Lrt_b_a_0_1_3
	v_add_u32_e32 v0, s46, v103
	v_mul_u32_u24_e32 v0, 0x6000, v0
	v_add_u32_e32 v0, v0, v101
	v_lshl_add_u64 v[116:117], s[50:51], 0, v[0:1]
	global_load_dwordx4 v[118:121], v[116:117], off offset:128
.Lrt_b_a_0_1_3:
	s_waitcnt vmcnt(0) lgkmcnt(0)
	v_pk_fma_f32 v[196:197], v[180:181], v[212:213], v[196:197]
	v_pk_fma_f32 v[198:199], v[182:183], v[214:215], v[198:199]
	v_pk_fma_f32 v[200:201], v[184:185], v[216:217], v[200:201]
	v_pk_fma_f32 v[202:203], v[186:187], v[218:219], v[202:203]
	v_pk_fma_f32 v[204:205], v[188:189], v[220:221], v[204:205]
	v_pk_fma_f32 v[206:207], v[190:191], v[222:223], v[206:207]
	v_pk_fma_f32 v[208:209], v[192:193], v[134:135], v[208:209]
	v_pk_fma_f32 v[210:211], v[194:195], v[136:137], v[210:211]
	global_store_dwordx4 v[104:105], v[196:199], off offset:128
	global_store_dwordx4 v[106:107], v[200:203], off offset:128
	global_store_dwordx4 v[108:109], v[204:207], off offset:128
	global_store_dwordx4 v[110:111], v[208:211], off offset:128
	s_and_b64 vcc, exec, s[52:53]
	s_cbranch_vccz .Lrt_b_x_0_1
	v_mul_f32_e32 v180, v196, v196
	v_fmac_f32_e32 v180, v197, v197
	v_fmac_f32_e32 v180, v198, v198
	v_fmac_f32_e32 v180, v199, v199
	v_pk_add_f32 v[138:139], v[138:139], 1.0 op_sel_hi:[1,0]
	v_pk_add_f32 v[140:141], v[140:141], 1.0 op_sel_hi:[1,0]
	v_pk_mul_f32 v[196:197], v[196:197], v[126:127]
	v_pk_mul_f32 v[198:199], v[198:199], v[128:129]
	v_pk_mul_f32 v[196:197], v[196:197], v[138:139]
	v_pk_mul_f32 v[198:199], v[198:199], v[140:141]
	v_cvt_pk_f16_f32 v196, v196, v197
	v_cvt_pk_f16_f32 v197, v198, v199
	v_add_u32_e32 v115, 0, v102
	v_lshlrev_b32_e32 v0, 12, v115
	v_add_u32_e32 v0, v0, v101
	v_lshrrev_b32_e32 v0, 1, v0
	v_lshl_add_u64 v[116:117], s[44:45], 0, v[0:1]
	global_store_dwordx2 v[116:117], v[196:197], off offset:64
	v_mul_f32_e32 v184, v200, v200
	v_fmac_f32_e32 v184, v201, v201
	v_fmac_f32_e32 v184, v202, v202
	v_fmac_f32_e32 v184, v203, v203
	v_pk_add_f32 v[142:143], v[142:143], 1.0 op_sel_hi:[1,0]
	v_pk_add_f32 v[144:145], v[144:145], 1.0 op_sel_hi:[1,0]
	v_pk_mul_f32 v[200:201], v[200:201], v[126:127]
	v_pk_mul_f32 v[202:203], v[202:203], v[128:129]
	v_pk_mul_f32 v[200:201], v[200:201], v[142:143]
	v_pk_mul_f32 v[202:203], v[202:203], v[144:145]
	v_cvt_pk_f16_f32 v200, v200, v201
	v_cvt_pk_f16_f32 v201, v202, v203
	v_add_u32_e32 v115, 8, v102
	v_lshlrev_b32_e32 v0, 12, v115
	v_add_u32_e32 v0, v0, v101
	v_lshrrev_b32_e32 v0, 1, v0
	v_lshl_add_u64 v[116:117], s[44:45], 0, v[0:1]
	global_store_dwordx2 v[116:117], v[200:201], off offset:64
	v_mul_f32_e32 v188, v204, v204
	v_fmac_f32_e32 v188, v205, v205
	v_fmac_f32_e32 v188, v206, v206
	v_fmac_f32_e32 v188, v207, v207
	v_pk_add_f32 v[146:147], v[146:147], 1.0 op_sel_hi:[1,0]
	v_pk_add_f32 v[148:149], v[148:149], 1.0 op_sel_hi:[1,0]
	v_pk_mul_f32 v[204:205], v[204:205], v[126:127]
	v_pk_mul_f32 v[206:207], v[206:207], v[128:129]
	v_pk_mul_f32 v[204:205], v[204:205], v[146:147]
	v_pk_mul_f32 v[206:207], v[206:207], v[148:149]
	v_cvt_pk_f16_f32 v204, v204, v205
	v_cvt_pk_f16_f32 v205, v206, v207
	v_add_u32_e32 v115, 16, v102
	v_lshlrev_b32_e32 v0, 12, v115
	v_add_u32_e32 v0, v0, v101
	v_lshrrev_b32_e32 v0, 1, v0
	v_lshl_add_u64 v[116:117], s[44:45], 0, v[0:1]
	global_store_dwordx2 v[116:117], v[204:205], off offset:64
	v_mul_f32_e32 v192, v208, v208
	v_fmac_f32_e32 v192, v209, v209
	v_fmac_f32_e32 v192, v210, v210
	v_fmac_f32_e32 v192, v211, v211
	v_pk_add_f32 v[118:119], v[118:119], 1.0 op_sel_hi:[1,0]
	v_pk_add_f32 v[120:121], v[120:121], 1.0 op_sel_hi:[1,0]
	v_pk_mul_f32 v[208:209], v[208:209], v[126:127]
	v_pk_mul_f32 v[210:211], v[210:211], v[128:129]
	v_pk_mul_f32 v[208:209], v[208:209], v[118:119]
	v_pk_mul_f32 v[210:211], v[210:211], v[120:121]
	v_cvt_pk_f16_f32 v208, v208, v209
	v_cvt_pk_f16_f32 v209, v210, v211
	v_add_u32_e32 v115, 24, v102
	v_lshlrev_b32_e32 v0, 12, v115
	v_add_u32_e32 v0, v0, v101
	v_lshrrev_b32_e32 v0, 1, v0
	v_lshl_add_u64 v[116:117], s[44:45], 0, v[0:1]
	global_store_dwordx2 v[116:117], v[208:209], off offset:64
	s_nop 1
	v_add_f32_dpp v180, v180, v180 quad_perm:[1,0,3,2] row_mask:0xf bank_mask:0xf bound_ctrl:1
	v_add_f32_dpp v184, v184, v184 quad_perm:[1,0,3,2] row_mask:0xf bank_mask:0xf bound_ctrl:1
	v_add_f32_dpp v188, v188, v188 quad_perm:[1,0,3,2] row_mask:0xf bank_mask:0xf bound_ctrl:1
	v_add_f32_dpp v192, v192, v192 quad_perm:[1,0,3,2] row_mask:0xf bank_mask:0xf bound_ctrl:1
	s_nop 1
	v_add_f32_dpp v180, v180, v180 quad_perm:[2,3,0,1] row_mask:0xf bank_mask:0xf bound_ctrl:1
	v_add_f32_dpp v184, v184, v184 quad_perm:[2,3,0,1] row_mask:0xf bank_mask:0xf bound_ctrl:1
	v_add_f32_dpp v188, v188, v188 quad_perm:[2,3,0,1] row_mask:0xf bank_mask:0xf bound_ctrl:1
	v_add_f32_dpp v192, v192, v192 quad_perm:[2,3,0,1] row_mask:0xf bank_mask:0xf bound_ctrl:1
	s_nop 1
	v_add_f32_dpp v180, v180, v180 row_half_mirror row_mask:0xf bank_mask:0xf bound_ctrl:1
	v_add_f32_dpp v184, v184, v184 row_half_mirror row_mask:0xf bank_mask:0xf bound_ctrl:1
	v_add_f32_dpp v188, v188, v188 row_half_mirror row_mask:0xf bank_mask:0xf bound_ctrl:1
	v_add_f32_dpp v192, v192, v192 row_half_mirror row_mask:0xf bank_mask:0xf bound_ctrl:1
	s_mov_b64 s[42:43], exec
	s_mov_b32 s20, 0x01010101
	s_mov_b32 exec_lo, s20
	s_mov_b32 exec_hi, s20
	v_add_u32_e32 v0, 0, v102
	v_lshlrev_b32_e32 v0, 2, v0
	v_lshl_add_u64 v[116:117], s[12:13], 0, v[0:1]
	global_atomic_add_f32 v[116:117], v180, off
	v_add_u32_e32 v0, 8, v102
	v_lshlrev_b32_e32 v0, 2, v0
	v_lshl_add_u64 v[116:117], s[12:13], 0, v[0:1]
	global_atomic_add_f32 v[116:117], v184, off
	v_add_u32_e32 v0, 16, v102
	v_lshlrev_b32_e32 v0, 2, v0
	v_lshl_add_u64 v[116:117], s[12:13], 0, v[0:1]
	global_atomic_add_f32 v[116:117], v188, off
	v_add_u32_e32 v0, 24, v102
	v_lshlrev_b32_e32 v0, 2, v0
	v_lshl_add_u64 v[116:117], s[12:13], 0, v[0:1]
	global_atomic_add_f32 v[116:117], v192, off
	s_mov_b64 exec, s[42:43]
.Lrt_b_x_0_1:
	ds_write_b128 v98, v[50:53] offset:0
	ds_write_b128 v98, v[54:57] offset:32
	ds_write_b128 v98, v[58:61] offset:64
	ds_write_b128 v98, v[62:65] offset:96
	ds_read_b128 v[180:183], v99 offset:0
	ds_read_b128 v[184:187], v99 offset:1152
	ds_read_b128 v[188:191], v99 offset:2304
	ds_read_b128 v[192:195], v99 offset:3456
	v_add_u32_e32 v115, 32, v102
	v_subrev_co_u32_e32 v103, vcc, 0x1000, v115
	v_lshrrev_b32_e32 v103, 11, v103
	v_add_u32_e32 v103, 1, v103
	s_nop 0
	v_cndmask_b32_e64 v103, v103, 0, vcc
	v_add_u32_e32 v0, s46, v103
	v_mul_u32_u24_e32 v0, 0x6000, v0
	v_add_u32_e32 v0, v0, v101
	v_lshl_add_u64 v[116:117], s[48:49], 0, v[0:1]
	global_load_dwordx4 v[212:215], v[116:117], off offset:0
	v_lshlrev_b32_e32 v0, 12, v115
	v_add_u32_e32 v0, v0, v101
	v_lshl_add_u64 v[104:105], s[8:9], 0, v[0:1]
	global_load_dwordx4 v[196:199], v[104:105], off offset:0
	s_and_b64 vcc, exec, s[52:53]
	s_cbranch_vccz .Lrt_b_a_1_0_0
	v_add_u32_e32 v0, s46, v103
	v_mul_u32_u24_e32 v0, 0x6000, v0
	v_add_u32_e32 v0, v0, v101
	v_lshl_add_u64 v[116:117], s[50:51], 0, v[0:1]
	global_load_dwordx4 v[138:141], v[116:117], off offset:0
.Lrt_b_a_1_0_0:
	v_add_u32_e32 v115, 40, v102
	v_subrev_co_u32_e32 v103, vcc, 0x1000, v115
	v_lshrrev_b32_e32 v103, 11, v103
	v_add_u32_e32 v103, 1, v103
	s_nop 0
	v_cndmask_b32_e64 v103, v103, 0, vcc
	v_add_u32_e32 v0, s46, v103
	v_mul_u32_u24_e32 v0, 0x6000, v0
	v_add_u32_e32 v0, v0, v101
	v_lshl_add_u64 v[116:117], s[48:49], 0, v[0:1]
	global_load_dwordx4 v[216:219], v[116:117], off offset:0
	v_lshlrev_b32_e32 v0, 12, v115
	v_add_u32_e32 v0, v0, v101
	v_lshl_add_u64 v[106:107], s[8:9], 0, v[0:1]
	global_load_dwordx4 v[200:203], v[106:107], off offset:0
	s_and_b64 vcc, exec, s[52:53]
	s_cbranch_vccz .Lrt_b_a_1_0_1
	v_add_u32_e32 v0, s46, v103
	v_mul_u32_u24_e32 v0, 0x6000, v0
	v_add_u32_e32 v0, v0, v101
	v_lshl_add_u64 v[116:117], s[50:51], 0, v[0:1]
	global_load_dwordx4 v[142:145], v[116:117], off offset:0
.Lrt_b_a_1_0_1:
	v_add_u32_e32 v115, 48, v102
	v_subrev_co_u32_e32 v103, vcc, 0x1000, v115
	v_lshrrev_b32_e32 v103, 11, v103
	v_add_u32_e32 v103, 1, v103
	s_nop 0
	v_cndmask_b32_e64 v103, v103, 0, vcc
	v_add_u32_e32 v0, s46, v103
	v_mul_u32_u24_e32 v0, 0x6000, v0
	v_add_u32_e32 v0, v0, v101
	v_lshl_add_u64 v[116:117], s[48:49], 0, v[0:1]
	global_load_dwordx4 v[220:223], v[116:117], off offset:0
	v_lshlrev_b32_e32 v0, 12, v115
	v_add_u32_e32 v0, v0, v101
	v_lshl_add_u64 v[108:109], s[8:9], 0, v[0:1]
	global_load_dwordx4 v[204:207], v[108:109], off offset:0
	s_and_b64 vcc, exec, s[52:53]
	s_cbranch_vccz .Lrt_b_a_1_0_2
	v_add_u32_e32 v0, s46, v103
	v_mul_u32_u24_e32 v0, 0x6000, v0
	v_add_u32_e32 v0, v0, v101
	v_lshl_add_u64 v[116:117], s[50:51], 0, v[0:1]
	global_load_dwordx4 v[146:149], v[116:117], off offset:0
.Lrt_b_a_1_0_2:
	v_add_u32_e32 v115, 56, v102
	v_subrev_co_u32_e32 v103, vcc, 0x1000, v115
	v_lshrrev_b32_e32 v103, 11, v103
	v_add_u32_e32 v103, 1, v103
	s_nop 0
	v_cndmask_b32_e64 v103, v103, 0, vcc
	v_add_u32_e32 v0, s46, v103
	v_mul_u32_u24_e32 v0, 0x6000, v0
	v_add_u32_e32 v0, v0, v101
	v_lshl_add_u64 v[116:117], s[48:49], 0, v[0:1]
	global_load_dwordx4 v[134:137], v[116:117], off offset:0
	v_lshlrev_b32_e32 v0, 12, v115
	v_add_u32_e32 v0, v0, v101
	v_lshl_add_u64 v[110:111], s[8:9], 0, v[0:1]
	global_load_dwordx4 v[208:211], v[110:111], off offset:0
	s_and_b64 vcc, exec, s[52:53]
	s_cbranch_vccz .Lrt_b_a_1_0_3
	v_add_u32_e32 v0, s46, v103
	v_mul_u32_u24_e32 v0, 0x6000, v0
	v_add_u32_e32 v0, v0, v101
	v_lshl_add_u64 v[116:117], s[50:51], 0, v[0:1]
	global_load_dwordx4 v[118:121], v[116:117], off offset:0
.Lrt_b_a_1_0_3:
	s_waitcnt vmcnt(0) lgkmcnt(0)
	v_pk_fma_f32 v[196:197], v[180:181], v[212:213], v[196:197]
	v_pk_fma_f32 v[198:199], v[182:183], v[214:215], v[198:199]
	v_pk_fma_f32 v[200:201], v[184:185], v[216:217], v[200:201]
	v_pk_fma_f32 v[202:203], v[186:187], v[218:219], v[202:203]
	v_pk_fma_f32 v[204:205], v[188:189], v[220:221], v[204:205]
	v_pk_fma_f32 v[206:207], v[190:191], v[222:223], v[206:207]
	v_pk_fma_f32 v[208:209], v[192:193], v[134:135], v[208:209]
	v_pk_fma_f32 v[210:211], v[194:195], v[136:137], v[210:211]
	global_store_dwordx4 v[104:105], v[196:199], off offset:0
	global_store_dwordx4 v[106:107], v[200:203], off offset:0
	global_store_dwordx4 v[108:109], v[204:207], off offset:0
	global_store_dwordx4 v[110:111], v[208:211], off offset:0
	s_and_b64 vcc, exec, s[52:53]
	s_cbranch_vccz .Lrt_b_x_1_0
	v_mul_f32_e32 v180, v196, v196
	v_fmac_f32_e32 v180, v197, v197
	v_fmac_f32_e32 v180, v198, v198
	v_fmac_f32_e32 v180, v199, v199
	v_pk_add_f32 v[138:139], v[138:139], 1.0 op_sel_hi:[1,0]
	v_pk_add_f32 v[140:141], v[140:141], 1.0 op_sel_hi:[1,0]
	v_pk_mul_f32 v[196:197], v[196:197], v[122:123]
	v_pk_mul_f32 v[198:199], v[198:199], v[124:125]
	v_pk_mul_f32 v[196:197], v[196:197], v[138:139]
	v_pk_mul_f32 v[198:199], v[198:199], v[140:141]
	v_cvt_pk_f16_f32 v196, v196, v197
	v_cvt_pk_f16_f32 v197, v198, v199
	v_add_u32_e32 v115, 32, v102
	v_lshlrev_b32_e32 v0, 12, v115
	v_add_u32_e32 v0, v0, v101
	v_lshrrev_b32_e32 v0, 1, v0
	v_lshl_add_u64 v[116:117], s[44:45], 0, v[0:1]
	global_store_dwordx2 v[116:117], v[196:197], off offset:0
	v_mul_f32_e32 v184, v200, v200
	v_fmac_f32_e32 v184, v201, v201
	v_fmac_f32_e32 v184, v202, v202
	v_fmac_f32_e32 v184, v203, v203
	v_pk_add_f32 v[142:143], v[142:143], 1.0 op_sel_hi:[1,0]
	v_pk_add_f32 v[144:145], v[144:145], 1.0 op_sel_hi:[1,0]
	v_pk_mul_f32 v[200:201], v[200:201], v[122:123]
	v_pk_mul_f32 v[202:203], v[202:203], v[124:125]
	v_pk_mul_f32 v[200:201], v[200:201], v[142:143]
	v_pk_mul_f32 v[202:203], v[202:203], v[144:145]
	v_cvt_pk_f16_f32 v200, v200, v201
	v_cvt_pk_f16_f32 v201, v202, v203
	v_add_u32_e32 v115, 40, v102
	v_lshlrev_b32_e32 v0, 12, v115
	v_add_u32_e32 v0, v0, v101
	v_lshrrev_b32_e32 v0, 1, v0
	v_lshl_add_u64 v[116:117], s[44:45], 0, v[0:1]
	global_store_dwordx2 v[116:117], v[200:201], off offset:0
	v_mul_f32_e32 v188, v204, v204
	v_fmac_f32_e32 v188, v205, v205
	v_fmac_f32_e32 v188, v206, v206
	v_fmac_f32_e32 v188, v207, v207
	v_pk_add_f32 v[146:147], v[146:147], 1.0 op_sel_hi:[1,0]
	v_pk_add_f32 v[148:149], v[148:149], 1.0 op_sel_hi:[1,0]
	v_pk_mul_f32 v[204:205], v[204:205], v[122:123]
	v_pk_mul_f32 v[206:207], v[206:207], v[124:125]
	v_pk_mul_f32 v[204:205], v[204:205], v[146:147]
	v_pk_mul_f32 v[206:207], v[206:207], v[148:149]
	v_cvt_pk_f16_f32 v204, v204, v205
	v_cvt_pk_f16_f32 v205, v206, v207
	v_add_u32_e32 v115, 48, v102
	v_lshlrev_b32_e32 v0, 12, v115
	v_add_u32_e32 v0, v0, v101
	v_lshrrev_b32_e32 v0, 1, v0
	v_lshl_add_u64 v[116:117], s[44:45], 0, v[0:1]
	global_store_dwordx2 v[116:117], v[204:205], off offset:0
	v_mul_f32_e32 v192, v208, v208
	v_fmac_f32_e32 v192, v209, v209
	v_fmac_f32_e32 v192, v210, v210
	v_fmac_f32_e32 v192, v211, v211
	v_pk_add_f32 v[118:119], v[118:119], 1.0 op_sel_hi:[1,0]
	v_pk_add_f32 v[120:121], v[120:121], 1.0 op_sel_hi:[1,0]
	v_pk_mul_f32 v[208:209], v[208:209], v[122:123]
	v_pk_mul_f32 v[210:211], v[210:211], v[124:125]
	v_pk_mul_f32 v[208:209], v[208:209], v[118:119]
	v_pk_mul_f32 v[210:211], v[210:211], v[120:121]
	v_cvt_pk_f16_f32 v208, v208, v209
	v_cvt_pk_f16_f32 v209, v210, v211
	v_add_u32_e32 v115, 56, v102
	v_lshlrev_b32_e32 v0, 12, v115
	v_add_u32_e32 v0, v0, v101
	v_lshrrev_b32_e32 v0, 1, v0
	v_lshl_add_u64 v[116:117], s[44:45], 0, v[0:1]
	global_store_dwordx2 v[116:117], v[208:209], off offset:0
	s_nop 1
	v_add_f32_dpp v180, v180, v180 quad_perm:[1,0,3,2] row_mask:0xf bank_mask:0xf bound_ctrl:1
	v_add_f32_dpp v184, v184, v184 quad_perm:[1,0,3,2] row_mask:0xf bank_mask:0xf bound_ctrl:1
	v_add_f32_dpp v188, v188, v188 quad_perm:[1,0,3,2] row_mask:0xf bank_mask:0xf bound_ctrl:1
	v_add_f32_dpp v192, v192, v192 quad_perm:[1,0,3,2] row_mask:0xf bank_mask:0xf bound_ctrl:1
	s_nop 1
	v_add_f32_dpp v180, v180, v180 quad_perm:[2,3,0,1] row_mask:0xf bank_mask:0xf bound_ctrl:1
	v_add_f32_dpp v184, v184, v184 quad_perm:[2,3,0,1] row_mask:0xf bank_mask:0xf bound_ctrl:1
	v_add_f32_dpp v188, v188, v188 quad_perm:[2,3,0,1] row_mask:0xf bank_mask:0xf bound_ctrl:1
	v_add_f32_dpp v192, v192, v192 quad_perm:[2,3,0,1] row_mask:0xf bank_mask:0xf bound_ctrl:1
	s_nop 1
	v_add_f32_dpp v180, v180, v180 row_half_mirror row_mask:0xf bank_mask:0xf bound_ctrl:1
	v_add_f32_dpp v184, v184, v184 row_half_mirror row_mask:0xf bank_mask:0xf bound_ctrl:1
	v_add_f32_dpp v188, v188, v188 row_half_mirror row_mask:0xf bank_mask:0xf bound_ctrl:1
	v_add_f32_dpp v192, v192, v192 row_half_mirror row_mask:0xf bank_mask:0xf bound_ctrl:1
	s_mov_b64 s[42:43], exec
	s_mov_b32 s20, 0x01010101
	s_mov_b32 exec_lo, s20
	s_mov_b32 exec_hi, s20
	v_add_u32_e32 v0, 32, v102
	v_lshlrev_b32_e32 v0, 2, v0
	v_lshl_add_u64 v[116:117], s[12:13], 0, v[0:1]
	global_atomic_add_f32 v[116:117], v180, off
	v_add_u32_e32 v0, 40, v102
	v_lshlrev_b32_e32 v0, 2, v0
	v_lshl_add_u64 v[116:117], s[12:13], 0, v[0:1]
	global_atomic_add_f32 v[116:117], v184, off
	v_add_u32_e32 v0, 48, v102
	v_lshlrev_b32_e32 v0, 2, v0
	v_lshl_add_u64 v[116:117], s[12:13], 0, v[0:1]
	global_atomic_add_f32 v[116:117], v188, off
	v_add_u32_e32 v0, 56, v102
	v_lshlrev_b32_e32 v0, 2, v0
	v_lshl_add_u64 v[116:117], s[12:13], 0, v[0:1]
	global_atomic_add_f32 v[116:117], v192, off
	s_mov_b64 exec, s[42:43]
.Lrt_b_x_1_0:
	ds_write_b128 v98, v[34:37] offset:4608
	ds_write_b128 v98, v[38:41] offset:4640
	ds_write_b128 v98, v[42:45] offset:4672
	ds_write_b128 v98, v[46:49] offset:4704
	ds_read_b128 v[180:183], v99 offset:4608
	ds_read_b128 v[184:187], v99 offset:5760
	ds_read_b128 v[188:191], v99 offset:6912
	ds_read_b128 v[192:195], v99 offset:8064
	v_add_u32_e32 v115, 32, v102
	v_subrev_co_u32_e32 v103, vcc, 0x1000, v115
	v_lshrrev_b32_e32 v103, 11, v103
	v_add_u32_e32 v103, 1, v103
	s_nop 0
	v_cndmask_b32_e64 v103, v103, 0, vcc
	v_add_u32_e32 v0, s46, v103
	v_mul_u32_u24_e32 v0, 0x6000, v0
	v_add_u32_e32 v0, v0, v101
	v_lshl_add_u64 v[116:117], s[48:49], 0, v[0:1]
	global_load_dwordx4 v[212:215], v[116:117], off offset:128
	v_lshlrev_b32_e32 v0, 12, v115
	v_add_u32_e32 v0, v0, v101
	v_lshl_add_u64 v[104:105], s[8:9], 0, v[0:1]
	global_load_dwordx4 v[196:199], v[104:105], off offset:128
	s_and_b64 vcc, exec, s[52:53]
	s_cbranch_vccz .Lrt_b_a_1_1_0
	v_add_u32_e32 v0, s46, v103
	v_mul_u32_u24_e32 v0, 0x6000, v0
	v_add_u32_e32 v0, v0, v101
	v_lshl_add_u64 v[116:117], s[50:51], 0, v[0:1]
	global_load_dwordx4 v[138:141], v[116:117], off offset:128
.Lrt_b_a_1_1_0:
	v_add_u32_e32 v115, 40, v102
	v_subrev_co_u32_e32 v103, vcc, 0x1000, v115
	v_lshrrev_b32_e32 v103, 11, v103
	v_add_u32_e32 v103, 1, v103
	s_nop 0
	v_cndmask_b32_e64 v103, v103, 0, vcc
	v_add_u32_e32 v0, s46, v103
	v_mul_u32_u24_e32 v0, 0x6000, v0
	v_add_u32_e32 v0, v0, v101
	v_lshl_add_u64 v[116:117], s[48:49], 0, v[0:1]
	global_load_dwordx4 v[216:219], v[116:117], off offset:128
	v_lshlrev_b32_e32 v0, 12, v115
	v_add_u32_e32 v0, v0, v101
	v_lshl_add_u64 v[106:107], s[8:9], 0, v[0:1]
	global_load_dwordx4 v[200:203], v[106:107], off offset:128
	s_and_b64 vcc, exec, s[52:53]
	s_cbranch_vccz .Lrt_b_a_1_1_1
	v_add_u32_e32 v0, s46, v103
	v_mul_u32_u24_e32 v0, 0x6000, v0
	v_add_u32_e32 v0, v0, v101
	v_lshl_add_u64 v[116:117], s[50:51], 0, v[0:1]
	global_load_dwordx4 v[142:145], v[116:117], off offset:128
.Lrt_b_a_1_1_1:
	v_add_u32_e32 v115, 48, v102
	v_subrev_co_u32_e32 v103, vcc, 0x1000, v115
	v_lshrrev_b32_e32 v103, 11, v103
	v_add_u32_e32 v103, 1, v103
	s_nop 0
	v_cndmask_b32_e64 v103, v103, 0, vcc
	v_add_u32_e32 v0, s46, v103
	v_mul_u32_u24_e32 v0, 0x6000, v0
	v_add_u32_e32 v0, v0, v101
	v_lshl_add_u64 v[116:117], s[48:49], 0, v[0:1]
	global_load_dwordx4 v[220:223], v[116:117], off offset:128
	v_lshlrev_b32_e32 v0, 12, v115
	v_add_u32_e32 v0, v0, v101
	v_lshl_add_u64 v[108:109], s[8:9], 0, v[0:1]
	global_load_dwordx4 v[204:207], v[108:109], off offset:128
	s_and_b64 vcc, exec, s[52:53]
	s_cbranch_vccz .Lrt_b_a_1_1_2
	v_add_u32_e32 v0, s46, v103
	v_mul_u32_u24_e32 v0, 0x6000, v0
	v_add_u32_e32 v0, v0, v101
	v_lshl_add_u64 v[116:117], s[50:51], 0, v[0:1]
	global_load_dwordx4 v[146:149], v[116:117], off offset:128
.Lrt_b_a_1_1_2:
	v_add_u32_e32 v115, 56, v102
	v_subrev_co_u32_e32 v103, vcc, 0x1000, v115
	v_lshrrev_b32_e32 v103, 11, v103
	v_add_u32_e32 v103, 1, v103
	s_nop 0
	v_cndmask_b32_e64 v103, v103, 0, vcc
	v_add_u32_e32 v0, s46, v103
	v_mul_u32_u24_e32 v0, 0x6000, v0
	v_add_u32_e32 v0, v0, v101
	v_lshl_add_u64 v[116:117], s[48:49], 0, v[0:1]
	global_load_dwordx4 v[134:137], v[116:117], off offset:128
	v_lshlrev_b32_e32 v0, 12, v115
	v_add_u32_e32 v0, v0, v101
	v_lshl_add_u64 v[110:111], s[8:9], 0, v[0:1]
	global_load_dwordx4 v[208:211], v[110:111], off offset:128
	s_and_b64 vcc, exec, s[52:53]
	s_cbranch_vccz .Lrt_b_a_1_1_3
	v_add_u32_e32 v0, s46, v103
	v_mul_u32_u24_e32 v0, 0x6000, v0
	v_add_u32_e32 v0, v0, v101
	v_lshl_add_u64 v[116:117], s[50:51], 0, v[0:1]
	global_load_dwordx4 v[118:121], v[116:117], off offset:128
.Lrt_b_a_1_1_3:
	s_waitcnt vmcnt(0) lgkmcnt(0)
	v_pk_fma_f32 v[196:197], v[180:181], v[212:213], v[196:197]
	v_pk_fma_f32 v[198:199], v[182:183], v[214:215], v[198:199]
	v_pk_fma_f32 v[200:201], v[184:185], v[216:217], v[200:201]
	v_pk_fma_f32 v[202:203], v[186:187], v[218:219], v[202:203]
	v_pk_fma_f32 v[204:205], v[188:189], v[220:221], v[204:205]
	v_pk_fma_f32 v[206:207], v[190:191], v[222:223], v[206:207]
	v_pk_fma_f32 v[208:209], v[192:193], v[134:135], v[208:209]
	v_pk_fma_f32 v[210:211], v[194:195], v[136:137], v[210:211]
	global_store_dwordx4 v[104:105], v[196:199], off offset:128
	global_store_dwordx4 v[106:107], v[200:203], off offset:128
	global_store_dwordx4 v[108:109], v[204:207], off offset:128
	global_store_dwordx4 v[110:111], v[208:211], off offset:128
	s_and_b64 vcc, exec, s[52:53]
	s_cbranch_vccz .Lrt_b_x_1_1
	v_mul_f32_e32 v180, v196, v196
	v_fmac_f32_e32 v180, v197, v197
	v_fmac_f32_e32 v180, v198, v198
	v_fmac_f32_e32 v180, v199, v199
	v_pk_add_f32 v[138:139], v[138:139], 1.0 op_sel_hi:[1,0]
	v_pk_add_f32 v[140:141], v[140:141], 1.0 op_sel_hi:[1,0]
	v_pk_mul_f32 v[196:197], v[196:197], v[126:127]
	v_pk_mul_f32 v[198:199], v[198:199], v[128:129]
	v_pk_mul_f32 v[196:197], v[196:197], v[138:139]
	v_pk_mul_f32 v[198:199], v[198:199], v[140:141]
	v_cvt_pk_f16_f32 v196, v196, v197
	v_cvt_pk_f16_f32 v197, v198, v199
	v_add_u32_e32 v115, 32, v102
	v_lshlrev_b32_e32 v0, 12, v115
	v_add_u32_e32 v0, v0, v101
	v_lshrrev_b32_e32 v0, 1, v0
	v_lshl_add_u64 v[116:117], s[44:45], 0, v[0:1]
	global_store_dwordx2 v[116:117], v[196:197], off offset:64
	v_mul_f32_e32 v184, v200, v200
	v_fmac_f32_e32 v184, v201, v201
	v_fmac_f32_e32 v184, v202, v202
	v_fmac_f32_e32 v184, v203, v203
	v_pk_add_f32 v[142:143], v[142:143], 1.0 op_sel_hi:[1,0]
	v_pk_add_f32 v[144:145], v[144:145], 1.0 op_sel_hi:[1,0]
	v_pk_mul_f32 v[200:201], v[200:201], v[126:127]
	v_pk_mul_f32 v[202:203], v[202:203], v[128:129]
	v_pk_mul_f32 v[200:201], v[200:201], v[142:143]
	v_pk_mul_f32 v[202:203], v[202:203], v[144:145]
	v_cvt_pk_f16_f32 v200, v200, v201
	v_cvt_pk_f16_f32 v201, v202, v203
	v_add_u32_e32 v115, 40, v102
	v_lshlrev_b32_e32 v0, 12, v115
	v_add_u32_e32 v0, v0, v101
	v_lshrrev_b32_e32 v0, 1, v0
	v_lshl_add_u64 v[116:117], s[44:45], 0, v[0:1]
	global_store_dwordx2 v[116:117], v[200:201], off offset:64
	v_mul_f32_e32 v188, v204, v204
	v_fmac_f32_e32 v188, v205, v205
	v_fmac_f32_e32 v188, v206, v206
	v_fmac_f32_e32 v188, v207, v207
	v_pk_add_f32 v[146:147], v[146:147], 1.0 op_sel_hi:[1,0]
	v_pk_add_f32 v[148:149], v[148:149], 1.0 op_sel_hi:[1,0]
	v_pk_mul_f32 v[204:205], v[204:205], v[126:127]
	v_pk_mul_f32 v[206:207], v[206:207], v[128:129]
	v_pk_mul_f32 v[204:205], v[204:205], v[146:147]
	v_pk_mul_f32 v[206:207], v[206:207], v[148:149]
	v_cvt_pk_f16_f32 v204, v204, v205
	v_cvt_pk_f16_f32 v205, v206, v207
	v_add_u32_e32 v115, 48, v102
	v_lshlrev_b32_e32 v0, 12, v115
	v_add_u32_e32 v0, v0, v101
	v_lshrrev_b32_e32 v0, 1, v0
	v_lshl_add_u64 v[116:117], s[44:45], 0, v[0:1]
	global_store_dwordx2 v[116:117], v[204:205], off offset:64
	v_mul_f32_e32 v192, v208, v208
	v_fmac_f32_e32 v192, v209, v209
	v_fmac_f32_e32 v192, v210, v210
	v_fmac_f32_e32 v192, v211, v211
	v_pk_add_f32 v[118:119], v[118:119], 1.0 op_sel_hi:[1,0]
	v_pk_add_f32 v[120:121], v[120:121], 1.0 op_sel_hi:[1,0]
	v_pk_mul_f32 v[208:209], v[208:209], v[126:127]
	v_pk_mul_f32 v[210:211], v[210:211], v[128:129]
	v_pk_mul_f32 v[208:209], v[208:209], v[118:119]
	v_pk_mul_f32 v[210:211], v[210:211], v[120:121]
	v_cvt_pk_f16_f32 v208, v208, v209
	v_cvt_pk_f16_f32 v209, v210, v211
	v_add_u32_e32 v115, 56, v102
	v_lshlrev_b32_e32 v0, 12, v115
	v_add_u32_e32 v0, v0, v101
	v_lshrrev_b32_e32 v0, 1, v0
	v_lshl_add_u64 v[116:117], s[44:45], 0, v[0:1]
	global_store_dwordx2 v[116:117], v[208:209], off offset:64
	s_nop 1
	v_add_f32_dpp v180, v180, v180 quad_perm:[1,0,3,2] row_mask:0xf bank_mask:0xf bound_ctrl:1
	v_add_f32_dpp v184, v184, v184 quad_perm:[1,0,3,2] row_mask:0xf bank_mask:0xf bound_ctrl:1
	v_add_f32_dpp v188, v188, v188 quad_perm:[1,0,3,2] row_mask:0xf bank_mask:0xf bound_ctrl:1
	v_add_f32_dpp v192, v192, v192 quad_perm:[1,0,3,2] row_mask:0xf bank_mask:0xf bound_ctrl:1
	s_nop 1
	v_add_f32_dpp v180, v180, v180 quad_perm:[2,3,0,1] row_mask:0xf bank_mask:0xf bound_ctrl:1
	v_add_f32_dpp v184, v184, v184 quad_perm:[2,3,0,1] row_mask:0xf bank_mask:0xf bound_ctrl:1
	v_add_f32_dpp v188, v188, v188 quad_perm:[2,3,0,1] row_mask:0xf bank_mask:0xf bound_ctrl:1
	v_add_f32_dpp v192, v192, v192 quad_perm:[2,3,0,1] row_mask:0xf bank_mask:0xf bound_ctrl:1
	s_nop 1
	v_add_f32_dpp v180, v180, v180 row_half_mirror row_mask:0xf bank_mask:0xf bound_ctrl:1
	v_add_f32_dpp v184, v184, v184 row_half_mirror row_mask:0xf bank_mask:0xf bound_ctrl:1
	v_add_f32_dpp v188, v188, v188 row_half_mirror row_mask:0xf bank_mask:0xf bound_ctrl:1
	v_add_f32_dpp v192, v192, v192 row_half_mirror row_mask:0xf bank_mask:0xf bound_ctrl:1
	s_mov_b64 s[42:43], exec
	s_mov_b32 s20, 0x01010101
	s_mov_b32 exec_lo, s20
	s_mov_b32 exec_hi, s20
	v_add_u32_e32 v0, 32, v102
	v_lshlrev_b32_e32 v0, 2, v0
	v_lshl_add_u64 v[116:117], s[12:13], 0, v[0:1]
	global_atomic_add_f32 v[116:117], v180, off
	v_add_u32_e32 v0, 40, v102
	v_lshlrev_b32_e32 v0, 2, v0
	v_lshl_add_u64 v[116:117], s[12:13], 0, v[0:1]
	global_atomic_add_f32 v[116:117], v184, off
	v_add_u32_e32 v0, 48, v102
	v_lshlrev_b32_e32 v0, 2, v0
	v_lshl_add_u64 v[116:117], s[12:13], 0, v[0:1]
	global_atomic_add_f32 v[116:117], v188, off
	v_add_u32_e32 v0, 56, v102
	v_lshlrev_b32_e32 v0, 2, v0
	v_lshl_add_u64 v[116:117], s[12:13], 0, v[0:1]
	global_atomic_add_f32 v[116:117], v192, off
	s_mov_b64 exec, s[42:43]
.Lrt_b_x_1_1:
	ds_write_b128 v98, v[18:21] offset:0
	ds_write_b128 v98, v[22:25] offset:32
	ds_write_b128 v98, v[26:29] offset:64
	ds_write_b128 v98, v[30:33] offset:96
	ds_read_b128 v[180:183], v99 offset:0
	ds_read_b128 v[184:187], v99 offset:1152
	ds_read_b128 v[188:191], v99 offset:2304
	ds_read_b128 v[192:195], v99 offset:3456
	v_add_u32_e32 v115, 64, v102
	v_subrev_co_u32_e32 v103, vcc, 0x1000, v115
	v_lshrrev_b32_e32 v103, 11, v103
	v_add_u32_e32 v103, 1, v103
	s_nop 0
	v_cndmask_b32_e64 v103, v103, 0, vcc
	v_add_u32_e32 v0, s46, v103
	v_mul_u32_u24_e32 v0, 0x6000, v0
	v_add_u32_e32 v0, v0, v101
	v_lshl_add_u64 v[116:117], s[48:49], 0, v[0:1]
	global_load_dwordx4 v[212:215], v[116:117], off offset:0
	v_lshlrev_b32_e32 v0, 12, v115
	v_add_u32_e32 v0, v0, v101
	v_lshl_add_u64 v[104:105], s[8:9], 0, v[0:1]
	global_load_dwordx4 v[196:199], v[104:105], off offset:0
	s_and_b64 vcc, exec, s[52:53]
	s_cbranch_vccz .Lrt_b_a_2_0_0
	v_add_u32_e32 v0, s46, v103
	v_mul_u32_u24_e32 v0, 0x6000, v0
	v_add_u32_e32 v0, v0, v101
	v_lshl_add_u64 v[116:117], s[50:51], 0, v[0:1]
	global_load_dwordx4 v[138:141], v[116:117], off offset:0
.Lrt_b_a_2_0_0:
	v_add_u32_e32 v115, 72, v102
	v_subrev_co_u32_e32 v103, vcc, 0x1000, v115
	v_lshrrev_b32_e32 v103, 11, v103
	v_add_u32_e32 v103, 1, v103
	s_nop 0
	v_cndmask_b32_e64 v103, v103, 0, vcc
	v_add_u32_e32 v0, s46, v103
	v_mul_u32_u24_e32 v0, 0x6000, v0
	v_add_u32_e32 v0, v0, v101
	v_lshl_add_u64 v[116:117], s[48:49], 0, v[0:1]
	global_load_dwordx4 v[216:219], v[116:117], off offset:0
	v_lshlrev_b32_e32 v0, 12, v115
	v_add_u32_e32 v0, v0, v101
	v_lshl_add_u64 v[106:107], s[8:9], 0, v[0:1]
	global_load_dwordx4 v[200:203], v[106:107], off offset:0
	s_and_b64 vcc, exec, s[52:53]
	s_cbranch_vccz .Lrt_b_a_2_0_1
	v_add_u32_e32 v0, s46, v103
	v_mul_u32_u24_e32 v0, 0x6000, v0
	v_add_u32_e32 v0, v0, v101
	v_lshl_add_u64 v[116:117], s[50:51], 0, v[0:1]
	global_load_dwordx4 v[142:145], v[116:117], off offset:0
.Lrt_b_a_2_0_1:
	v_add_u32_e32 v115, 80, v102
	v_subrev_co_u32_e32 v103, vcc, 0x1000, v115
	v_lshrrev_b32_e32 v103, 11, v103
	v_add_u32_e32 v103, 1, v103
	s_nop 0
	v_cndmask_b32_e64 v103, v103, 0, vcc
	v_add_u32_e32 v0, s46, v103
	v_mul_u32_u24_e32 v0, 0x6000, v0
	v_add_u32_e32 v0, v0, v101
	v_lshl_add_u64 v[116:117], s[48:49], 0, v[0:1]
	global_load_dwordx4 v[220:223], v[116:117], off offset:0
	v_lshlrev_b32_e32 v0, 12, v115
	v_add_u32_e32 v0, v0, v101
	v_lshl_add_u64 v[108:109], s[8:9], 0, v[0:1]
	global_load_dwordx4 v[204:207], v[108:109], off offset:0
	s_and_b64 vcc, exec, s[52:53]
	s_cbranch_vccz .Lrt_b_a_2_0_2
	v_add_u32_e32 v0, s46, v103
	v_mul_u32_u24_e32 v0, 0x6000, v0
	v_add_u32_e32 v0, v0, v101
	v_lshl_add_u64 v[116:117], s[50:51], 0, v[0:1]
	global_load_dwordx4 v[146:149], v[116:117], off offset:0
.Lrt_b_a_2_0_2:
	v_add_u32_e32 v115, 88, v102
	v_subrev_co_u32_e32 v103, vcc, 0x1000, v115
	v_lshrrev_b32_e32 v103, 11, v103
	v_add_u32_e32 v103, 1, v103
	s_nop 0
	v_cndmask_b32_e64 v103, v103, 0, vcc
	v_add_u32_e32 v0, s46, v103
	v_mul_u32_u24_e32 v0, 0x6000, v0
	v_add_u32_e32 v0, v0, v101
	v_lshl_add_u64 v[116:117], s[48:49], 0, v[0:1]
	global_load_dwordx4 v[134:137], v[116:117], off offset:0
	v_lshlrev_b32_e32 v0, 12, v115
	v_add_u32_e32 v0, v0, v101
	v_lshl_add_u64 v[110:111], s[8:9], 0, v[0:1]
	global_load_dwordx4 v[208:211], v[110:111], off offset:0
	s_and_b64 vcc, exec, s[52:53]
	s_cbranch_vccz .Lrt_b_a_2_0_3
	v_add_u32_e32 v0, s46, v103
	v_mul_u32_u24_e32 v0, 0x6000, v0
	v_add_u32_e32 v0, v0, v101
	v_lshl_add_u64 v[116:117], s[50:51], 0, v[0:1]
	global_load_dwordx4 v[118:121], v[116:117], off offset:0
.Lrt_b_a_2_0_3:
	s_waitcnt vmcnt(0) lgkmcnt(0)
	v_pk_fma_f32 v[196:197], v[180:181], v[212:213], v[196:197]
	v_pk_fma_f32 v[198:199], v[182:183], v[214:215], v[198:199]
	v_pk_fma_f32 v[200:201], v[184:185], v[216:217], v[200:201]
	v_pk_fma_f32 v[202:203], v[186:187], v[218:219], v[202:203]
	v_pk_fma_f32 v[204:205], v[188:189], v[220:221], v[204:205]
	v_pk_fma_f32 v[206:207], v[190:191], v[222:223], v[206:207]
	v_pk_fma_f32 v[208:209], v[192:193], v[134:135], v[208:209]
	v_pk_fma_f32 v[210:211], v[194:195], v[136:137], v[210:211]
	global_store_dwordx4 v[104:105], v[196:199], off offset:0
	global_store_dwordx4 v[106:107], v[200:203], off offset:0
	global_store_dwordx4 v[108:109], v[204:207], off offset:0
	global_store_dwordx4 v[110:111], v[208:211], off offset:0
	s_and_b64 vcc, exec, s[52:53]
	s_cbranch_vccz .Lrt_b_x_2_0
	v_mul_f32_e32 v180, v196, v196
	v_fmac_f32_e32 v180, v197, v197
	v_fmac_f32_e32 v180, v198, v198
	v_fmac_f32_e32 v180, v199, v199
	v_pk_add_f32 v[138:139], v[138:139], 1.0 op_sel_hi:[1,0]
	v_pk_add_f32 v[140:141], v[140:141], 1.0 op_sel_hi:[1,0]
	v_pk_mul_f32 v[196:197], v[196:197], v[122:123]
	v_pk_mul_f32 v[198:199], v[198:199], v[124:125]
	v_pk_mul_f32 v[196:197], v[196:197], v[138:139]
	v_pk_mul_f32 v[198:199], v[198:199], v[140:141]
	v_cvt_pk_f16_f32 v196, v196, v197
	v_cvt_pk_f16_f32 v197, v198, v199
	v_add_u32_e32 v115, 64, v102
	v_lshlrev_b32_e32 v0, 12, v115
	v_add_u32_e32 v0, v0, v101
	v_lshrrev_b32_e32 v0, 1, v0
	v_lshl_add_u64 v[116:117], s[44:45], 0, v[0:1]
	global_store_dwordx2 v[116:117], v[196:197], off offset:0
	v_mul_f32_e32 v184, v200, v200
	v_fmac_f32_e32 v184, v201, v201
	v_fmac_f32_e32 v184, v202, v202
	v_fmac_f32_e32 v184, v203, v203
	v_pk_add_f32 v[142:143], v[142:143], 1.0 op_sel_hi:[1,0]
	v_pk_add_f32 v[144:145], v[144:145], 1.0 op_sel_hi:[1,0]
	v_pk_mul_f32 v[200:201], v[200:201], v[122:123]
	v_pk_mul_f32 v[202:203], v[202:203], v[124:125]
	v_pk_mul_f32 v[200:201], v[200:201], v[142:143]
	v_pk_mul_f32 v[202:203], v[202:203], v[144:145]
	v_cvt_pk_f16_f32 v200, v200, v201
	v_cvt_pk_f16_f32 v201, v202, v203
	v_add_u32_e32 v115, 72, v102
	v_lshlrev_b32_e32 v0, 12, v115
	v_add_u32_e32 v0, v0, v101
	v_lshrrev_b32_e32 v0, 1, v0
	v_lshl_add_u64 v[116:117], s[44:45], 0, v[0:1]
	global_store_dwordx2 v[116:117], v[200:201], off offset:0
	v_mul_f32_e32 v188, v204, v204
	v_fmac_f32_e32 v188, v205, v205
	v_fmac_f32_e32 v188, v206, v206
	v_fmac_f32_e32 v188, v207, v207
	v_pk_add_f32 v[146:147], v[146:147], 1.0 op_sel_hi:[1,0]
	v_pk_add_f32 v[148:149], v[148:149], 1.0 op_sel_hi:[1,0]
	v_pk_mul_f32 v[204:205], v[204:205], v[122:123]
	v_pk_mul_f32 v[206:207], v[206:207], v[124:125]
	v_pk_mul_f32 v[204:205], v[204:205], v[146:147]
	v_pk_mul_f32 v[206:207], v[206:207], v[148:149]
	v_cvt_pk_f16_f32 v204, v204, v205
	v_cvt_pk_f16_f32 v205, v206, v207
	v_add_u32_e32 v115, 80, v102
	v_lshlrev_b32_e32 v0, 12, v115
	v_add_u32_e32 v0, v0, v101
	v_lshrrev_b32_e32 v0, 1, v0
	v_lshl_add_u64 v[116:117], s[44:45], 0, v[0:1]
	global_store_dwordx2 v[116:117], v[204:205], off offset:0
	v_mul_f32_e32 v192, v208, v208
	v_fmac_f32_e32 v192, v209, v209
	v_fmac_f32_e32 v192, v210, v210
	v_fmac_f32_e32 v192, v211, v211
	v_pk_add_f32 v[118:119], v[118:119], 1.0 op_sel_hi:[1,0]
	v_pk_add_f32 v[120:121], v[120:121], 1.0 op_sel_hi:[1,0]
	v_pk_mul_f32 v[208:209], v[208:209], v[122:123]
	v_pk_mul_f32 v[210:211], v[210:211], v[124:125]
	v_pk_mul_f32 v[208:209], v[208:209], v[118:119]
	v_pk_mul_f32 v[210:211], v[210:211], v[120:121]
	v_cvt_pk_f16_f32 v208, v208, v209
	v_cvt_pk_f16_f32 v209, v210, v211
	v_add_u32_e32 v115, 88, v102
	v_lshlrev_b32_e32 v0, 12, v115
	v_add_u32_e32 v0, v0, v101
	v_lshrrev_b32_e32 v0, 1, v0
	v_lshl_add_u64 v[116:117], s[44:45], 0, v[0:1]
	global_store_dwordx2 v[116:117], v[208:209], off offset:0
	s_nop 1
	v_add_f32_dpp v180, v180, v180 quad_perm:[1,0,3,2] row_mask:0xf bank_mask:0xf bound_ctrl:1
	v_add_f32_dpp v184, v184, v184 quad_perm:[1,0,3,2] row_mask:0xf bank_mask:0xf bound_ctrl:1
	v_add_f32_dpp v188, v188, v188 quad_perm:[1,0,3,2] row_mask:0xf bank_mask:0xf bound_ctrl:1
	v_add_f32_dpp v192, v192, v192 quad_perm:[1,0,3,2] row_mask:0xf bank_mask:0xf bound_ctrl:1
	s_nop 1
	v_add_f32_dpp v180, v180, v180 quad_perm:[2,3,0,1] row_mask:0xf bank_mask:0xf bound_ctrl:1
	v_add_f32_dpp v184, v184, v184 quad_perm:[2,3,0,1] row_mask:0xf bank_mask:0xf bound_ctrl:1
	v_add_f32_dpp v188, v188, v188 quad_perm:[2,3,0,1] row_mask:0xf bank_mask:0xf bound_ctrl:1
	v_add_f32_dpp v192, v192, v192 quad_perm:[2,3,0,1] row_mask:0xf bank_mask:0xf bound_ctrl:1
	s_nop 1
	v_add_f32_dpp v180, v180, v180 row_half_mirror row_mask:0xf bank_mask:0xf bound_ctrl:1
	v_add_f32_dpp v184, v184, v184 row_half_mirror row_mask:0xf bank_mask:0xf bound_ctrl:1
	v_add_f32_dpp v188, v188, v188 row_half_mirror row_mask:0xf bank_mask:0xf bound_ctrl:1
	v_add_f32_dpp v192, v192, v192 row_half_mirror row_mask:0xf bank_mask:0xf bound_ctrl:1
	s_mov_b64 s[42:43], exec
	s_mov_b32 s20, 0x01010101
	s_mov_b32 exec_lo, s20
	s_mov_b32 exec_hi, s20
	v_add_u32_e32 v0, 64, v102
	v_lshlrev_b32_e32 v0, 2, v0
	v_lshl_add_u64 v[116:117], s[12:13], 0, v[0:1]
	global_atomic_add_f32 v[116:117], v180, off
	v_add_u32_e32 v0, 72, v102
	v_lshlrev_b32_e32 v0, 2, v0
	v_lshl_add_u64 v[116:117], s[12:13], 0, v[0:1]
	global_atomic_add_f32 v[116:117], v184, off
	v_add_u32_e32 v0, 80, v102
	v_lshlrev_b32_e32 v0, 2, v0
	v_lshl_add_u64 v[116:117], s[12:13], 0, v[0:1]
	global_atomic_add_f32 v[116:117], v188, off
	v_add_u32_e32 v0, 88, v102
	v_lshlrev_b32_e32 v0, 2, v0
	v_lshl_add_u64 v[116:117], s[12:13], 0, v[0:1]
	global_atomic_add_f32 v[116:117], v192, off
	s_mov_b64 exec, s[42:43]
.Lrt_b_x_2_0:
	ds_write_b128 v98, v[2:5] offset:4608
	ds_write_b128 v98, v[6:9] offset:4640
	ds_write_b128 v98, v[10:13] offset:4672
	ds_write_b128 v98, v[14:17] offset:4704
	ds_read_b128 v[180:183], v99 offset:4608
	ds_read_b128 v[184:187], v99 offset:5760
	ds_read_b128 v[188:191], v99 offset:6912
	ds_read_b128 v[192:195], v99 offset:8064
	v_add_u32_e32 v115, 64, v102
	v_subrev_co_u32_e32 v103, vcc, 0x1000, v115
	v_lshrrev_b32_e32 v103, 11, v103
	v_add_u32_e32 v103, 1, v103
	s_nop 0
	v_cndmask_b32_e64 v103, v103, 0, vcc
	v_add_u32_e32 v0, s46, v103
	v_mul_u32_u24_e32 v0, 0x6000, v0
	v_add_u32_e32 v0, v0, v101
	v_lshl_add_u64 v[116:117], s[48:49], 0, v[0:1]
	global_load_dwordx4 v[212:215], v[116:117], off offset:128
	v_lshlrev_b32_e32 v0, 12, v115
	v_add_u32_e32 v0, v0, v101
	v_lshl_add_u64 v[104:105], s[8:9], 0, v[0:1]
	global_load_dwordx4 v[196:199], v[104:105], off offset:128
	s_and_b64 vcc, exec, s[52:53]
	s_cbranch_vccz .Lrt_b_a_2_1_0
	v_add_u32_e32 v0, s46, v103
	v_mul_u32_u24_e32 v0, 0x6000, v0
	v_add_u32_e32 v0, v0, v101
	v_lshl_add_u64 v[116:117], s[50:51], 0, v[0:1]
	global_load_dwordx4 v[138:141], v[116:117], off offset:128
.Lrt_b_a_2_1_0:
	v_add_u32_e32 v115, 72, v102
	v_subrev_co_u32_e32 v103, vcc, 0x1000, v115
	v_lshrrev_b32_e32 v103, 11, v103
	v_add_u32_e32 v103, 1, v103
	s_nop 0
	v_cndmask_b32_e64 v103, v103, 0, vcc
	v_add_u32_e32 v0, s46, v103
	v_mul_u32_u24_e32 v0, 0x6000, v0
	v_add_u32_e32 v0, v0, v101
	v_lshl_add_u64 v[116:117], s[48:49], 0, v[0:1]
	global_load_dwordx4 v[216:219], v[116:117], off offset:128
	v_lshlrev_b32_e32 v0, 12, v115
	v_add_u32_e32 v0, v0, v101
	v_lshl_add_u64 v[106:107], s[8:9], 0, v[0:1]
	global_load_dwordx4 v[200:203], v[106:107], off offset:128
	s_and_b64 vcc, exec, s[52:53]
	s_cbranch_vccz .Lrt_b_a_2_1_1
	v_add_u32_e32 v0, s46, v103
	v_mul_u32_u24_e32 v0, 0x6000, v0
	v_add_u32_e32 v0, v0, v101
	v_lshl_add_u64 v[116:117], s[50:51], 0, v[0:1]
	global_load_dwordx4 v[142:145], v[116:117], off offset:128
.Lrt_b_a_2_1_1:
	v_add_u32_e32 v115, 80, v102
	v_subrev_co_u32_e32 v103, vcc, 0x1000, v115
	v_lshrrev_b32_e32 v103, 11, v103
	v_add_u32_e32 v103, 1, v103
	s_nop 0
	v_cndmask_b32_e64 v103, v103, 0, vcc
	v_add_u32_e32 v0, s46, v103
	v_mul_u32_u24_e32 v0, 0x6000, v0
	v_add_u32_e32 v0, v0, v101
	v_lshl_add_u64 v[116:117], s[48:49], 0, v[0:1]
	global_load_dwordx4 v[220:223], v[116:117], off offset:128
	v_lshlrev_b32_e32 v0, 12, v115
	v_add_u32_e32 v0, v0, v101
	v_lshl_add_u64 v[108:109], s[8:9], 0, v[0:1]
	global_load_dwordx4 v[204:207], v[108:109], off offset:128
	s_and_b64 vcc, exec, s[52:53]
	s_cbranch_vccz .Lrt_b_a_2_1_2
	v_add_u32_e32 v0, s46, v103
	v_mul_u32_u24_e32 v0, 0x6000, v0
	v_add_u32_e32 v0, v0, v101
	v_lshl_add_u64 v[116:117], s[50:51], 0, v[0:1]
	global_load_dwordx4 v[146:149], v[116:117], off offset:128
.Lrt_b_a_2_1_2:
	v_add_u32_e32 v115, 88, v102
	v_subrev_co_u32_e32 v103, vcc, 0x1000, v115
	v_lshrrev_b32_e32 v103, 11, v103
	v_add_u32_e32 v103, 1, v103
	s_nop 0
	v_cndmask_b32_e64 v103, v103, 0, vcc
	v_add_u32_e32 v0, s46, v103
	v_mul_u32_u24_e32 v0, 0x6000, v0
	v_add_u32_e32 v0, v0, v101
	v_lshl_add_u64 v[116:117], s[48:49], 0, v[0:1]
	global_load_dwordx4 v[134:137], v[116:117], off offset:128
	v_lshlrev_b32_e32 v0, 12, v115
	v_add_u32_e32 v0, v0, v101
	v_lshl_add_u64 v[110:111], s[8:9], 0, v[0:1]
	global_load_dwordx4 v[208:211], v[110:111], off offset:128
	s_and_b64 vcc, exec, s[52:53]
	s_cbranch_vccz .Lrt_b_a_2_1_3
	v_add_u32_e32 v0, s46, v103
	v_mul_u32_u24_e32 v0, 0x6000, v0
	v_add_u32_e32 v0, v0, v101
	v_lshl_add_u64 v[116:117], s[50:51], 0, v[0:1]
	global_load_dwordx4 v[118:121], v[116:117], off offset:128
.Lrt_b_a_2_1_3:
	s_waitcnt vmcnt(0) lgkmcnt(0)
	v_pk_fma_f32 v[196:197], v[180:181], v[212:213], v[196:197]
	v_pk_fma_f32 v[198:199], v[182:183], v[214:215], v[198:199]
	v_pk_fma_f32 v[200:201], v[184:185], v[216:217], v[200:201]
	v_pk_fma_f32 v[202:203], v[186:187], v[218:219], v[202:203]
	v_pk_fma_f32 v[204:205], v[188:189], v[220:221], v[204:205]
	v_pk_fma_f32 v[206:207], v[190:191], v[222:223], v[206:207]
	v_pk_fma_f32 v[208:209], v[192:193], v[134:135], v[208:209]
	v_pk_fma_f32 v[210:211], v[194:195], v[136:137], v[210:211]
	global_store_dwordx4 v[104:105], v[196:199], off offset:128
	global_store_dwordx4 v[106:107], v[200:203], off offset:128
	global_store_dwordx4 v[108:109], v[204:207], off offset:128
	global_store_dwordx4 v[110:111], v[208:211], off offset:128
	s_and_b64 vcc, exec, s[52:53]
	s_cbranch_vccz .Lrt_b_x_2_1
	v_mul_f32_e32 v180, v196, v196
	v_fmac_f32_e32 v180, v197, v197
	v_fmac_f32_e32 v180, v198, v198
	v_fmac_f32_e32 v180, v199, v199
	v_pk_add_f32 v[138:139], v[138:139], 1.0 op_sel_hi:[1,0]
	v_pk_add_f32 v[140:141], v[140:141], 1.0 op_sel_hi:[1,0]
	v_pk_mul_f32 v[196:197], v[196:197], v[126:127]
	v_pk_mul_f32 v[198:199], v[198:199], v[128:129]
	v_pk_mul_f32 v[196:197], v[196:197], v[138:139]
	v_pk_mul_f32 v[198:199], v[198:199], v[140:141]
	v_cvt_pk_f16_f32 v196, v196, v197
	v_cvt_pk_f16_f32 v197, v198, v199
	v_add_u32_e32 v115, 64, v102
	v_lshlrev_b32_e32 v0, 12, v115
	v_add_u32_e32 v0, v0, v101
	v_lshrrev_b32_e32 v0, 1, v0
	v_lshl_add_u64 v[116:117], s[44:45], 0, v[0:1]
	global_store_dwordx2 v[116:117], v[196:197], off offset:64
	v_mul_f32_e32 v184, v200, v200
	v_fmac_f32_e32 v184, v201, v201
	v_fmac_f32_e32 v184, v202, v202
	v_fmac_f32_e32 v184, v203, v203
	v_pk_add_f32 v[142:143], v[142:143], 1.0 op_sel_hi:[1,0]
	v_pk_add_f32 v[144:145], v[144:145], 1.0 op_sel_hi:[1,0]
	v_pk_mul_f32 v[200:201], v[200:201], v[126:127]
	v_pk_mul_f32 v[202:203], v[202:203], v[128:129]
	v_pk_mul_f32 v[200:201], v[200:201], v[142:143]
	v_pk_mul_f32 v[202:203], v[202:203], v[144:145]
	v_cvt_pk_f16_f32 v200, v200, v201
	v_cvt_pk_f16_f32 v201, v202, v203
	v_add_u32_e32 v115, 72, v102
	v_lshlrev_b32_e32 v0, 12, v115
	v_add_u32_e32 v0, v0, v101
	v_lshrrev_b32_e32 v0, 1, v0
	v_lshl_add_u64 v[116:117], s[44:45], 0, v[0:1]
	global_store_dwordx2 v[116:117], v[200:201], off offset:64
	v_mul_f32_e32 v188, v204, v204
	v_fmac_f32_e32 v188, v205, v205
	v_fmac_f32_e32 v188, v206, v206
	v_fmac_f32_e32 v188, v207, v207
	v_pk_add_f32 v[146:147], v[146:147], 1.0 op_sel_hi:[1,0]
	v_pk_add_f32 v[148:149], v[148:149], 1.0 op_sel_hi:[1,0]
	v_pk_mul_f32 v[204:205], v[204:205], v[126:127]
	v_pk_mul_f32 v[206:207], v[206:207], v[128:129]
	v_pk_mul_f32 v[204:205], v[204:205], v[146:147]
	v_pk_mul_f32 v[206:207], v[206:207], v[148:149]
	v_cvt_pk_f16_f32 v204, v204, v205
	v_cvt_pk_f16_f32 v205, v206, v207
	v_add_u32_e32 v115, 80, v102
	v_lshlrev_b32_e32 v0, 12, v115
	v_add_u32_e32 v0, v0, v101
	v_lshrrev_b32_e32 v0, 1, v0
	v_lshl_add_u64 v[116:117], s[44:45], 0, v[0:1]
	global_store_dwordx2 v[116:117], v[204:205], off offset:64
	v_mul_f32_e32 v192, v208, v208
	v_fmac_f32_e32 v192, v209, v209
	v_fmac_f32_e32 v192, v210, v210
	v_fmac_f32_e32 v192, v211, v211
	v_pk_add_f32 v[118:119], v[118:119], 1.0 op_sel_hi:[1,0]
	v_pk_add_f32 v[120:121], v[120:121], 1.0 op_sel_hi:[1,0]
	v_pk_mul_f32 v[208:209], v[208:209], v[126:127]
	v_pk_mul_f32 v[210:211], v[210:211], v[128:129]
	v_pk_mul_f32 v[208:209], v[208:209], v[118:119]
	v_pk_mul_f32 v[210:211], v[210:211], v[120:121]
	v_cvt_pk_f16_f32 v208, v208, v209
	v_cvt_pk_f16_f32 v209, v210, v211
	v_add_u32_e32 v115, 88, v102
	v_lshlrev_b32_e32 v0, 12, v115
	v_add_u32_e32 v0, v0, v101
	v_lshrrev_b32_e32 v0, 1, v0
	v_lshl_add_u64 v[116:117], s[44:45], 0, v[0:1]
	global_store_dwordx2 v[116:117], v[208:209], off offset:64
	s_nop 1
	v_add_f32_dpp v180, v180, v180 quad_perm:[1,0,3,2] row_mask:0xf bank_mask:0xf bound_ctrl:1
	v_add_f32_dpp v184, v184, v184 quad_perm:[1,0,3,2] row_mask:0xf bank_mask:0xf bound_ctrl:1
	v_add_f32_dpp v188, v188, v188 quad_perm:[1,0,3,2] row_mask:0xf bank_mask:0xf bound_ctrl:1
	v_add_f32_dpp v192, v192, v192 quad_perm:[1,0,3,2] row_mask:0xf bank_mask:0xf bound_ctrl:1
	s_nop 1
	v_add_f32_dpp v180, v180, v180 quad_perm:[2,3,0,1] row_mask:0xf bank_mask:0xf bound_ctrl:1
	v_add_f32_dpp v184, v184, v184 quad_perm:[2,3,0,1] row_mask:0xf bank_mask:0xf bound_ctrl:1
	v_add_f32_dpp v188, v188, v188 quad_perm:[2,3,0,1] row_mask:0xf bank_mask:0xf bound_ctrl:1
	v_add_f32_dpp v192, v192, v192 quad_perm:[2,3,0,1] row_mask:0xf bank_mask:0xf bound_ctrl:1
	s_nop 1
	v_add_f32_dpp v180, v180, v180 row_half_mirror row_mask:0xf bank_mask:0xf bound_ctrl:1
	v_add_f32_dpp v184, v184, v184 row_half_mirror row_mask:0xf bank_mask:0xf bound_ctrl:1
	v_add_f32_dpp v188, v188, v188 row_half_mirror row_mask:0xf bank_mask:0xf bound_ctrl:1
	v_add_f32_dpp v192, v192, v192 row_half_mirror row_mask:0xf bank_mask:0xf bound_ctrl:1
	s_mov_b64 s[42:43], exec
	s_mov_b32 s20, 0x01010101
	s_mov_b32 exec_lo, s20
	s_mov_b32 exec_hi, s20
	v_add_u32_e32 v0, 64, v102
	v_lshlrev_b32_e32 v0, 2, v0
	v_lshl_add_u64 v[116:117], s[12:13], 0, v[0:1]
	global_atomic_add_f32 v[116:117], v180, off
	v_add_u32_e32 v0, 72, v102
	v_lshlrev_b32_e32 v0, 2, v0
	v_lshl_add_u64 v[116:117], s[12:13], 0, v[0:1]
	global_atomic_add_f32 v[116:117], v184, off
	v_add_u32_e32 v0, 80, v102
	v_lshlrev_b32_e32 v0, 2, v0
	v_lshl_add_u64 v[116:117], s[12:13], 0, v[0:1]
	global_atomic_add_f32 v[116:117], v188, off
	v_add_u32_e32 v0, 88, v102
	v_lshlrev_b32_e32 v0, 2, v0
	v_lshl_add_u64 v[116:117], s[12:13], 0, v[0:1]
	global_atomic_add_f32 v[116:117], v192, off
	s_mov_b64 exec, s[42:43]
.Lrt_b_x_2_1:
	s_waitcnt vmcnt(0)
	s_branch .LBB0_131
.LBB0_196:
	v_readlane_b32 s54, v224, 28
	v_readlane_b32 s55, v224, 29
	s_mov_b32 s88, 0x800000
